# SwiGLU epilogue (F1a,F2a): packed f32 mul/add, batched exp/rcp (8 independent chains), no hazard nops; same arithmetic
# speedup vs baseline: 1.0102x; 1.0102x over previous
; __device__ __forceinline__ unsigned cvt_pk_bf16(float lo, float hi) { unsigned r; asm volatile("v_cvt_pk_bf16_f32 %0, %1, %2" : "=v"(r) : "v"(lo), "v"(hi)); return r; }
; __device__ __forceinline__ float fast_sigmoid(float x) { return __builtin_amdgcn_rcpf(1.0f + __builtin_amdgcn_exp2f(-1.4426950408889634f * x)); }
; __device__ __forceinline__ u32x4 pack8(const f32x4 v0, const f32x4 v1) { u32x4 w; w.x = cvt_pk_bf16(v0[0], v0[1]); w.y = cvt_pk_bf16(v0[2], v0[3]); w.z = cvt_pk_bf16(v1[0], v1[1]); w.w = cvt_pk_bf16(v1[2], v1[3]); return w; }
;     __device__ __forceinline__ void operator()(const f32x4 (&acc)[2][2][4][2], const Unit& u, int wr, int wc, int fr_, int fq) const {
;     ...
;                 for (int j = 0; j < 4; ++j) { const float g0 = acc[ai][0][m][0][j], g1 = acc[ai][0][m][1][j];
;                     v0[j] = g0 * fast_sigmoid(g0) * acc[ai][1][m][0][j]; v1[j] = g1 * fast_sigmoid(g1) * acc[ai][1][m][1][j]; }
;                 *(u32x4*)(Hblk + (size_t)(ai * HALF + m * 16) * BK) = pack8(v0, v1); }
.LBB0_219:
	v_mov_b32_e32 v184, 0xbfb8aa3b
	v_mov_b32_e32 v185, 0xbfb8aa3b
	v_mov_b32_e32 v188, 1.0
	v_mov_b32_e32 v189, 1.0
	v_pk_mul_f32 v[190:191], v[126:127], v[184:185]
	v_pk_mul_f32 v[192:193], v[128:129], v[184:185]
	v_pk_mul_f32 v[224:225], v[118:119], v[184:185]
	v_pk_mul_f32 v[226:227], v[120:121], v[184:185]
	v_exp_f32_e32 v190, v190
	v_exp_f32_e32 v191, v191
	v_exp_f32_e32 v192, v192
	v_exp_f32_e32 v193, v193
	v_exp_f32_e32 v224, v224
	v_exp_f32_e32 v225, v225
	v_exp_f32_e32 v226, v226
	v_exp_f32_e32 v227, v227
	v_pk_add_f32 v[190:191], v[190:191], v[188:189]
	v_pk_add_f32 v[192:193], v[192:193], v[188:189]
	v_pk_add_f32 v[224:225], v[224:225], v[188:189]
	v_pk_add_f32 v[226:227], v[226:227], v[188:189]
	v_rcp_f32_e32 v190, v190
	v_rcp_f32_e32 v191, v191
	v_rcp_f32_e32 v192, v192
	v_rcp_f32_e32 v193, v193
	v_rcp_f32_e32 v224, v224
	v_rcp_f32_e32 v225, v225
	v_rcp_f32_e32 v226, v226
	v_rcp_f32_e32 v227, v227
	v_pk_mul_f32 v[126:127], v[126:127], v[190:191]
	v_pk_mul_f32 v[128:129], v[128:129], v[192:193]
	v_pk_mul_f32 v[118:119], v[118:119], v[224:225]
	v_pk_mul_f32 v[120:121], v[120:121], v[226:227]
	v_pk_mul_f32 v[126:127], v[126:127], v[122:123]
	v_pk_mul_f32 v[128:129], v[128:129], v[124:125]
	v_pk_mul_f32 v[118:119], v[118:119], v[114:115]
	v_pk_mul_f32 v[120:121], v[120:121], v[116:117]
	v_cvt_pk_bf16_f32 v114, v126, v127
	v_cvt_pk_bf16_f32 v115, v128, v129
	v_cvt_pk_bf16_f32 v116, v118, v119
	v_cvt_pk_bf16_f32 v117, v120, v121
	s_lshl_b32 s1, s1, 1
	s_mulk_i32 s0, 0x58
	s_or_b32 s1, s1, s56
	s_add_i32 s0, s1, s0
	v_mov_b32_e32 v142, v144
	s_ashr_i32 s1, s0, 31
	s_lshl_b64 s[0:1], s[0:1], 15
	v_ashrrev_i32_e32 v143, 31, v142
	v_lshl_add_u64 v[142:143], v[142:143], 0, s[8:9]
	s_add_u32 s0, s47, s0
	v_lshlrev_b64 v[142:143], 7, v[142:143]
	s_addc_u32 s1, s50, s1
	v_lshl_add_u64 v[142:143], s[0:1], 0, v[142:143]
	v_lshl_add_u64 v[142:143], v[142:143], 0, s[16:17]
	v_lshl_add_u64 v[142:143], v[142:143], 0, v[186:187]
	s_movk_i32 s0, 0x5000
	global_store_dwordx4 v[142:143], v[114:117], off
	v_pk_mul_f32 v[190:191], v[110:111], v[184:185]
	v_pk_mul_f32 v[192:193], v[112:113], v[184:185]
	v_pk_mul_f32 v[224:225], v[102:103], v[184:185]
	v_pk_mul_f32 v[226:227], v[104:105], v[184:185]
	v_exp_f32_e32 v190, v190
	v_exp_f32_e32 v191, v191
	v_exp_f32_e32 v192, v192
	v_exp_f32_e32 v193, v193
	v_exp_f32_e32 v224, v224
	v_exp_f32_e32 v225, v225
	v_exp_f32_e32 v226, v226
	v_exp_f32_e32 v227, v227
	v_pk_add_f32 v[190:191], v[190:191], v[188:189]
	v_pk_add_f32 v[192:193], v[192:193], v[188:189]
	v_pk_add_f32 v[224:225], v[224:225], v[188:189]
	v_pk_add_f32 v[226:227], v[226:227], v[188:189]
	v_rcp_f32_e32 v190, v190
	v_rcp_f32_e32 v191, v191
	v_rcp_f32_e32 v192, v192
	v_rcp_f32_e32 v193, v193
	v_rcp_f32_e32 v224, v224
	v_rcp_f32_e32 v225, v225
	v_rcp_f32_e32 v226, v226
	v_rcp_f32_e32 v227, v227
	v_pk_mul_f32 v[110:111], v[110:111], v[190:191]
	v_pk_mul_f32 v[112:113], v[112:113], v[192:193]
	v_pk_mul_f32 v[102:103], v[102:103], v[224:225]
	v_pk_mul_f32 v[104:105], v[104:105], v[226:227]
	v_pk_mul_f32 v[110:111], v[110:111], v[106:107]
	v_pk_mul_f32 v[112:113], v[112:113], v[108:109]
	v_pk_mul_f32 v[102:103], v[102:103], v[98:99]
	v_pk_mul_f32 v[104:105], v[104:105], v[100:101]
	v_cvt_pk_bf16_f32 v98, v110, v111
	v_cvt_pk_bf16_f32 v99, v112, v113
	v_cvt_pk_bf16_f32 v100, v102, v103
	v_cvt_pk_bf16_f32 v101, v104, v105
	global_store_dwordx4 v[142:143], v[98:101], off offset:2048
	v_pk_mul_f32 v[190:191], v[94:95], v[184:185]
	v_pk_mul_f32 v[192:193], v[96:97], v[184:185]
	v_pk_mul_f32 v[224:225], v[86:87], v[184:185]
	v_pk_mul_f32 v[226:227], v[88:89], v[184:185]
	v_exp_f32_e32 v190, v190
	v_exp_f32_e32 v191, v191
	v_exp_f32_e32 v192, v192
	v_exp_f32_e32 v193, v193
	v_exp_f32_e32 v224, v224
	v_exp_f32_e32 v225, v225
	v_exp_f32_e32 v226, v226
	v_exp_f32_e32 v227, v227
	v_pk_add_f32 v[190:191], v[190:191], v[188:189]
	v_pk_add_f32 v[192:193], v[192:193], v[188:189]
	v_pk_add_f32 v[224:225], v[224:225], v[188:189]
	v_pk_add_f32 v[226:227], v[226:227], v[188:189]
	v_rcp_f32_e32 v190, v190
	v_rcp_f32_e32 v191, v191
	v_rcp_f32_e32 v192, v192
	v_rcp_f32_e32 v193, v193
	v_rcp_f32_e32 v224, v224
	v_rcp_f32_e32 v225, v225
	v_rcp_f32_e32 v226, v226
	v_rcp_f32_e32 v227, v227
	v_pk_mul_f32 v[94:95], v[94:95], v[190:191]
	v_pk_mul_f32 v[96:97], v[96:97], v[192:193]
	v_pk_mul_f32 v[86:87], v[86:87], v[224:225]
	v_pk_mul_f32 v[88:89], v[88:89], v[226:227]
	v_pk_mul_f32 v[94:95], v[94:95], v[90:91]
	v_pk_mul_f32 v[96:97], v[96:97], v[92:93]
	v_pk_mul_f32 v[86:87], v[86:87], v[82:83]
	v_pk_mul_f32 v[88:89], v[88:89], v[84:85]
	v_cvt_pk_bf16_f32 v82, v94, v95
	v_cvt_pk_bf16_f32 v83, v96, v97
	v_cvt_pk_bf16_f32 v84, v86, v87
	v_cvt_pk_bf16_f32 v85, v88, v89
	v_add_co_u32_e32 v86, vcc, s67, v142
	s_nop 1
	v_addc_co_u32_e32 v87, vcc, 0, v143, vcc
	global_store_dwordx4 v[86:87], v[82:85], off
	v_pk_mul_f32 v[190:191], v[78:79], v[184:185]
	v_pk_mul_f32 v[192:193], v[80:81], v[184:185]
	v_pk_mul_f32 v[224:225], v[70:71], v[184:185]
	v_pk_mul_f32 v[226:227], v[72:73], v[184:185]
	v_exp_f32_e32 v190, v190
	v_exp_f32_e32 v191, v191
	v_exp_f32_e32 v192, v192
	v_exp_f32_e32 v193, v193
	v_exp_f32_e32 v224, v224
	v_exp_f32_e32 v225, v225
	v_exp_f32_e32 v226, v226
	v_exp_f32_e32 v227, v227
	v_pk_add_f32 v[190:191], v[190:191], v[188:189]
	v_pk_add_f32 v[192:193], v[192:193], v[188:189]
	v_pk_add_f32 v[224:225], v[224:225], v[188:189]
	v_pk_add_f32 v[226:227], v[226:227], v[188:189]
	v_rcp_f32_e32 v190, v190
	v_rcp_f32_e32 v191, v191
	v_rcp_f32_e32 v192, v192
	v_rcp_f32_e32 v193, v193
	v_rcp_f32_e32 v224, v224
	v_rcp_f32_e32 v225, v225
	v_rcp_f32_e32 v226, v226
; __device__ __forceinline__ float fast_sigmoid(float x) { return __builtin_amdgcn_rcpf(1.0f + __builtin_amdgcn_exp2f(-1.4426950408889634f * x)); }
; __device__ __forceinline__ u32x4 pack8(const f32x4 v0, const f32x4 v1) { u32x4 w; w.x = cvt_pk_bf16(v0[0], v0[1]); w.y = cvt_pk_bf16(v0[2], v0[3]); w.z = cvt_pk_bf16(v1[0], v1[1]); w.w = cvt_pk_bf16(v1[2], v1[3]); return w; }
; #define PG8_BAR __builtin_amdgcn_s_barrier()
;     __device__ __forceinline__ void operator()(const f32x4 (&acc)[2][2][4][2], const Unit& u, int wr, int wc, int fr_, int fq) const {
;     ...
;                 for (int j = 0; j < 4; ++j) { const float g0 = acc[ai][0][m][0][j], g1 = acc[ai][0][m][1][j];
;                     v0[j] = g0 * fast_sigmoid(g0) * acc[ai][1][m][0][j]; v1[j] = g1 * fast_sigmoid(g1) * acc[ai][1][m][1][j]; }
;                 *(u32x4*)(Hblk + (size_t)(ai * HALF + m * 16) * BK) = pack8(v0, v1); }
; template <class Epi, class Sched, bool ALIGN_EPI = false, bool SP2 = false, bool ABLK = false, bool BBLK = false>
; __device__ __forceinline__ void gemm_phase(PG8_LAS unsigned char* lds, const Gemm g, const Sched& S, const Epi& E) {
;     ...
;         if (!has_next) break;
; #pragma unroll
;         for (int a = 0; a < 2; ++a)
; #pragma unroll
;             for (int b = 0; b < 2; ++b)
; #pragma unroll
;                 for (int m = 0; m < 4; ++m)
; #pragma unroll
;                     for (int n = 0; n < 2; ++n) acc[a][b][m][n] = (f32x4){0.f, 0.f, 0.f, 0.f};
;         cur = nxt; cA = nA; cB = nB; ++ui;
;         if constexpr (ALIGN_EPI) { if (wr == 1) PG8_BAR; }
	v_rcp_f32_e32 v227, v227
	v_pk_mul_f32 v[78:79], v[78:79], v[190:191]
	v_pk_mul_f32 v[80:81], v[80:81], v[192:193]
	v_pk_mul_f32 v[70:71], v[70:71], v[224:225]
	v_pk_mul_f32 v[72:73], v[72:73], v[226:227]
	v_pk_mul_f32 v[78:79], v[78:79], v[74:75]
	v_pk_mul_f32 v[80:81], v[80:81], v[76:77]
	v_pk_mul_f32 v[70:71], v[70:71], v[66:67]
	v_pk_mul_f32 v[72:73], v[72:73], v[68:69]
	v_cvt_pk_bf16_f32 v66, v78, v79
	v_cvt_pk_bf16_f32 v67, v80, v81
	v_cvt_pk_bf16_f32 v68, v70, v71
	v_cvt_pk_bf16_f32 v69, v72, v73
	global_store_dwordx4 v[86:87], v[66:69], off offset:2048
	v_pk_mul_f32 v[190:191], v[62:63], v[184:185]
	v_pk_mul_f32 v[192:193], v[64:65], v[184:185]
	v_pk_mul_f32 v[224:225], v[54:55], v[184:185]
	v_pk_mul_f32 v[226:227], v[56:57], v[184:185]
	v_exp_f32_e32 v190, v190
	v_exp_f32_e32 v191, v191
	v_exp_f32_e32 v192, v192
	v_exp_f32_e32 v193, v193
	v_exp_f32_e32 v224, v224
	v_exp_f32_e32 v225, v225
	v_exp_f32_e32 v226, v226
	v_exp_f32_e32 v227, v227
	v_pk_add_f32 v[190:191], v[190:191], v[188:189]
	v_pk_add_f32 v[192:193], v[192:193], v[188:189]
	v_pk_add_f32 v[224:225], v[224:225], v[188:189]
	v_pk_add_f32 v[226:227], v[226:227], v[188:189]
	v_rcp_f32_e32 v190, v190
	v_rcp_f32_e32 v191, v191
	v_rcp_f32_e32 v192, v192
	v_rcp_f32_e32 v193, v193
	v_rcp_f32_e32 v224, v224
	v_rcp_f32_e32 v225, v225
	v_rcp_f32_e32 v226, v226
	v_rcp_f32_e32 v227, v227
	v_pk_mul_f32 v[62:63], v[62:63], v[190:191]
	v_pk_mul_f32 v[64:65], v[64:65], v[192:193]
	v_pk_mul_f32 v[54:55], v[54:55], v[224:225]
	v_pk_mul_f32 v[56:57], v[56:57], v[226:227]
	v_pk_mul_f32 v[62:63], v[62:63], v[58:59]
	v_pk_mul_f32 v[64:65], v[64:65], v[60:61]
	v_pk_mul_f32 v[54:55], v[54:55], v[50:51]
	v_pk_mul_f32 v[56:57], v[56:57], v[52:53]
	v_cvt_pk_bf16_f32 v52, v62, v63
	v_cvt_pk_bf16_f32 v53, v64, v65
	v_cvt_pk_bf16_f32 v54, v54, v55
	v_cvt_pk_bf16_f32 v55, v56, v57
	v_add_co_u32_e32 v56, vcc, s87, v142
	s_nop 1
	v_addc_co_u32_e32 v57, vcc, 0, v143, vcc
	v_add_co_u32_e32 v50, vcc, s0, v142
	s_nop 1
	s_mov_b64 s[0:1], -1
	v_addc_co_u32_e32 v51, vcc, 0, v143, vcc
	global_store_dwordx4 v[50:51], v[52:55], off offset:-4096
	v_pk_mul_f32 v[190:191], v[46:47], v[184:185]
	v_pk_mul_f32 v[192:193], v[48:49], v[184:185]
	v_pk_mul_f32 v[224:225], v[38:39], v[184:185]
	v_pk_mul_f32 v[226:227], v[40:41], v[184:185]
	v_exp_f32_e32 v190, v190
	v_exp_f32_e32 v191, v191
	v_exp_f32_e32 v192, v192
	v_exp_f32_e32 v193, v193
	v_exp_f32_e32 v224, v224
	v_exp_f32_e32 v225, v225
	v_exp_f32_e32 v226, v226
	v_exp_f32_e32 v227, v227
	v_pk_add_f32 v[190:191], v[190:191], v[188:189]
	v_pk_add_f32 v[192:193], v[192:193], v[188:189]
	v_pk_add_f32 v[224:225], v[224:225], v[188:189]
	v_pk_add_f32 v[226:227], v[226:227], v[188:189]
	v_rcp_f32_e32 v190, v190
	v_rcp_f32_e32 v191, v191
	v_rcp_f32_e32 v192, v192
	v_rcp_f32_e32 v193, v193
	v_rcp_f32_e32 v224, v224
	v_rcp_f32_e32 v225, v225
	v_rcp_f32_e32 v226, v226
	v_rcp_f32_e32 v227, v227
	v_pk_mul_f32 v[46:47], v[46:47], v[190:191]
	v_pk_mul_f32 v[48:49], v[48:49], v[192:193]
	v_pk_mul_f32 v[38:39], v[38:39], v[224:225]
	v_pk_mul_f32 v[40:41], v[40:41], v[226:227]
	v_pk_mul_f32 v[46:47], v[46:47], v[42:43]
	v_pk_mul_f32 v[48:49], v[48:49], v[44:45]
	v_pk_mul_f32 v[38:39], v[38:39], v[34:35]
	v_pk_mul_f32 v[40:41], v[40:41], v[36:37]
	v_cvt_pk_bf16_f32 v34, v46, v47
	v_cvt_pk_bf16_f32 v35, v48, v49
	v_cvt_pk_bf16_f32 v36, v38, v39
	v_cvt_pk_bf16_f32 v37, v40, v41
	s_andn2_b64 vcc, exec, s[4:5]
	global_store_dwordx4 v[56:57], v[34:37], off offset:2048
	v_pk_mul_f32 v[190:191], v[30:31], v[184:185]
	v_pk_mul_f32 v[192:193], v[32:33], v[184:185]
	v_pk_mul_f32 v[224:225], v[22:23], v[184:185]
	v_pk_mul_f32 v[226:227], v[24:25], v[184:185]
	v_exp_f32_e32 v190, v190
	v_exp_f32_e32 v191, v191
	v_exp_f32_e32 v192, v192
	v_exp_f32_e32 v193, v193
	v_exp_f32_e32 v224, v224
	v_exp_f32_e32 v225, v225
	v_exp_f32_e32 v226, v226
	v_exp_f32_e32 v227, v227
	v_pk_add_f32 v[190:191], v[190:191], v[188:189]
	v_pk_add_f32 v[192:193], v[192:193], v[188:189]
	v_pk_add_f32 v[224:225], v[224:225], v[188:189]
	v_pk_add_f32 v[226:227], v[226:227], v[188:189]
	v_rcp_f32_e32 v190, v190
	v_rcp_f32_e32 v191, v191
	v_rcp_f32_e32 v192, v192
	v_rcp_f32_e32 v193, v193
	v_rcp_f32_e32 v224, v224
	v_rcp_f32_e32 v225, v225
	v_rcp_f32_e32 v226, v226
	v_rcp_f32_e32 v227, v227
	v_pk_mul_f32 v[30:31], v[30:31], v[190:191]
	v_pk_mul_f32 v[32:33], v[32:33], v[192:193]
	v_pk_mul_f32 v[22:23], v[22:23], v[224:225]
	v_pk_mul_f32 v[24:25], v[24:25], v[226:227]
	v_pk_mul_f32 v[30:31], v[30:31], v[26:27]
	v_pk_mul_f32 v[32:33], v[32:33], v[28:29]
	v_pk_mul_f32 v[22:23], v[22:23], v[18:19]
	v_pk_mul_f32 v[24:25], v[24:25], v[20:21]
	v_cvt_pk_bf16_f32 v18, v30, v31
	v_cvt_pk_bf16_f32 v19, v32, v33
	v_cvt_pk_bf16_f32 v20, v22, v23
	v_cvt_pk_bf16_f32 v21, v24, v25
	global_store_dwordx4 v[50:51], v[18:21], off
	v_pk_mul_f32 v[190:191], v[14:15], v[184:185]
	v_pk_mul_f32 v[192:193], v[16:17], v[184:185]
	v_pk_mul_f32 v[224:225], v[6:7], v[184:185]
	v_pk_mul_f32 v[226:227], v[8:9], v[184:185]
	v_exp_f32_e32 v190, v190
	v_exp_f32_e32 v191, v191
	v_exp_f32_e32 v192, v192
	v_exp_f32_e32 v193, v193
	v_exp_f32_e32 v224, v224
	v_exp_f32_e32 v225, v225
	v_exp_f32_e32 v226, v226
	v_exp_f32_e32 v227, v227
	v_pk_add_f32 v[190:191], v[190:191], v[188:189]
	v_pk_add_f32 v[192:193], v[192:193], v[188:189]
	v_pk_add_f32 v[224:225], v[224:225], v[188:189]
	v_pk_add_f32 v[226:227], v[226:227], v[188:189]
	v_rcp_f32_e32 v190, v190
	v_rcp_f32_e32 v191, v191
	v_rcp_f32_e32 v192, v192
	v_rcp_f32_e32 v193, v193
	v_rcp_f32_e32 v224, v224
	v_rcp_f32_e32 v225, v225
	v_rcp_f32_e32 v226, v226
	v_rcp_f32_e32 v227, v227
	v_pk_mul_f32 v[14:15], v[14:15], v[190:191]
	v_pk_mul_f32 v[16:17], v[16:17], v[192:193]
	v_pk_mul_f32 v[6:7], v[6:7], v[224:225]
	v_pk_mul_f32 v[8:9], v[8:9], v[226:227]
	v_pk_mul_f32 v[14:15], v[14:15], v[10:11]
	v_pk_mul_f32 v[16:17], v[16:17], v[12:13]
	v_pk_mul_f32 v[6:7], v[6:7], v[2:3]
	v_pk_mul_f32 v[8:9], v[8:9], v[4:5]
	v_cvt_pk_bf16_f32 v2, v14, v15
	v_cvt_pk_bf16_f32 v3, v16, v17
	v_cvt_pk_bf16_f32 v4, v6, v7
	v_cvt_pk_bf16_f32 v5, v8, v9
	global_store_dwordx4 v[50:51], v[2:5], off offset:2048
	s_cbranch_vccnz .LBB0_212
	s_andn2_b64 vcc, exec, s[6:7]
	s_cbranch_vccnz .LBB0_211
	s_barrier
	s_branch .LBB0_211

; __device__ __forceinline__ unsigned cvt_pk_bf16(float lo, float hi) { unsigned r; asm volatile("v_cvt_pk_bf16_f32 %0, %1, %2" : "=v"(r) : "v"(lo), "v"(hi)); return r; }
; __device__ __forceinline__ float fast_sigmoid(float x) { return __builtin_amdgcn_rcpf(1.0f + __builtin_amdgcn_exp2f(-1.4426950408889634f * x)); }
; __device__ __forceinline__ u32x4 pack8(const f32x4 v0, const f32x4 v1) { u32x4 w; w.x = cvt_pk_bf16(v0[0], v0[1]); w.y = cvt_pk_bf16(v0[2], v0[3]); w.z = cvt_pk_bf16(v1[0], v1[1]); w.w = cvt_pk_bf16(v1[2], v1[3]); return w; }
;     __device__ __forceinline__ void operator()(const f32x4 (&acc)[2][2][4][2], const Unit& u, int wr, int wc, int fr_, int fq) const {
;     ...
;                 for (int j = 0; j < 4; ++j) { const float g0 = acc[ai][0][m][0][j], g1 = acc[ai][0][m][1][j];
;                     v0[j] = g0 * fast_sigmoid(g0) * acc[ai][1][m][0][j]; v1[j] = g1 * fast_sigmoid(g1) * acc[ai][1][m][1][j]; }
;                 *(u32x4*)(Hblk + (size_t)(ai * HALF + m * 16) * BK) = pack8(v0, v1); }
.LBB0_1343:
	v_mov_b32_e32 v184, 0xbfb8aa3b
	v_mov_b32_e32 v185, 0xbfb8aa3b
	v_mov_b32_e32 v188, 1.0
	v_mov_b32_e32 v189, 1.0
	v_pk_mul_f32 v[190:191], v[126:127], v[184:185]
	v_pk_mul_f32 v[192:193], v[128:129], v[184:185]
	v_pk_mul_f32 v[224:225], v[118:119], v[184:185]
	v_pk_mul_f32 v[226:227], v[120:121], v[184:185]
	v_exp_f32_e32 v190, v190
	v_exp_f32_e32 v191, v191
	v_exp_f32_e32 v192, v192
	v_exp_f32_e32 v193, v193
	v_exp_f32_e32 v224, v224
	v_exp_f32_e32 v225, v225
	v_exp_f32_e32 v226, v226
	v_exp_f32_e32 v227, v227
	v_pk_add_f32 v[190:191], v[190:191], v[188:189]
	v_pk_add_f32 v[192:193], v[192:193], v[188:189]
	v_pk_add_f32 v[224:225], v[224:225], v[188:189]
	v_pk_add_f32 v[226:227], v[226:227], v[188:189]
	v_rcp_f32_e32 v190, v190
	v_rcp_f32_e32 v191, v191
	v_rcp_f32_e32 v192, v192
	v_rcp_f32_e32 v193, v193
	v_rcp_f32_e32 v224, v224
	v_rcp_f32_e32 v225, v225
	v_rcp_f32_e32 v226, v226
	v_rcp_f32_e32 v227, v227
	v_pk_mul_f32 v[126:127], v[126:127], v[190:191]
	v_pk_mul_f32 v[128:129], v[128:129], v[192:193]
	v_pk_mul_f32 v[118:119], v[118:119], v[224:225]
	v_pk_mul_f32 v[120:121], v[120:121], v[226:227]
	v_pk_mul_f32 v[126:127], v[126:127], v[122:123]
	v_pk_mul_f32 v[128:129], v[128:129], v[124:125]
	v_pk_mul_f32 v[118:119], v[118:119], v[114:115]
	v_pk_mul_f32 v[120:121], v[120:121], v[116:117]
	v_cvt_pk_bf16_f32 v114, v126, v127
	v_cvt_pk_bf16_f32 v115, v128, v129
	v_cvt_pk_bf16_f32 v116, v118, v119
	v_cvt_pk_bf16_f32 v117, v120, v121
	s_lshl_b32 s0, s0, 1
	s_mul_i32 s1, s24, 0x58
	s_or_b32 s0, s0, s61
	s_add_i32 s0, s0, s1
	v_mov_b32_e32 v142, v144
	s_ashr_i32 s1, s0, 31
	s_lshl_b64 s[0:1], s[0:1], 15
	v_ashrrev_i32_e32 v143, 31, v142
	v_lshl_add_u64 v[142:143], v[142:143], 0, s[8:9]
	s_add_u32 s0, s51, s0
	v_lshlrev_b64 v[142:143], 7, v[142:143]
	s_addc_u32 s1, s53, s1
	v_lshl_add_u64 v[142:143], s[0:1], 0, v[142:143]
	v_lshl_add_u64 v[142:143], v[142:143], 0, s[16:17]
	v_lshl_add_u64 v[142:143], v[142:143], 0, v[186:187]
	s_movk_i32 s0, 0x5000
	s_mov_b32 s88, 0xf800000
	s_movk_i32 s89, 0xffe0
	s_mov_b32 s52, 0x80000
	global_store_dwordx4 v[142:143], v[114:117], off
	v_pk_mul_f32 v[190:191], v[110:111], v[184:185]
	v_pk_mul_f32 v[192:193], v[112:113], v[184:185]
	v_pk_mul_f32 v[224:225], v[102:103], v[184:185]
	v_pk_mul_f32 v[226:227], v[104:105], v[184:185]
	v_exp_f32_e32 v190, v190
	v_exp_f32_e32 v191, v191
	v_exp_f32_e32 v192, v192
	v_exp_f32_e32 v193, v193
	v_exp_f32_e32 v224, v224
	v_exp_f32_e32 v225, v225
	v_exp_f32_e32 v226, v226
	v_exp_f32_e32 v227, v227
	v_pk_add_f32 v[190:191], v[190:191], v[188:189]
	v_pk_add_f32 v[192:193], v[192:193], v[188:189]
	v_pk_add_f32 v[224:225], v[224:225], v[188:189]
	v_pk_add_f32 v[226:227], v[226:227], v[188:189]
	v_rcp_f32_e32 v190, v190
	v_rcp_f32_e32 v191, v191
	v_rcp_f32_e32 v192, v192
	v_rcp_f32_e32 v193, v193
	v_rcp_f32_e32 v224, v224
	v_rcp_f32_e32 v225, v225
	v_rcp_f32_e32 v226, v226
	v_rcp_f32_e32 v227, v227
	v_pk_mul_f32 v[110:111], v[110:111], v[190:191]
	v_pk_mul_f32 v[112:113], v[112:113], v[192:193]
	v_pk_mul_f32 v[102:103], v[102:103], v[224:225]
	v_pk_mul_f32 v[104:105], v[104:105], v[226:227]
	v_pk_mul_f32 v[110:111], v[110:111], v[106:107]
	v_pk_mul_f32 v[112:113], v[112:113], v[108:109]
	v_pk_mul_f32 v[102:103], v[102:103], v[98:99]
	v_pk_mul_f32 v[104:105], v[104:105], v[100:101]
	v_cvt_pk_bf16_f32 v98, v110, v111
	v_cvt_pk_bf16_f32 v99, v112, v113
	v_cvt_pk_bf16_f32 v100, v102, v103
	v_cvt_pk_bf16_f32 v101, v104, v105
	global_store_dwordx4 v[142:143], v[98:101], off offset:2048
	v_pk_mul_f32 v[190:191], v[94:95], v[184:185]
	v_pk_mul_f32 v[192:193], v[96:97], v[184:185]
	v_pk_mul_f32 v[224:225], v[86:87], v[184:185]
	v_pk_mul_f32 v[226:227], v[88:89], v[184:185]
	v_exp_f32_e32 v190, v190
	v_exp_f32_e32 v191, v191
	v_exp_f32_e32 v192, v192
	v_exp_f32_e32 v193, v193
	v_exp_f32_e32 v224, v224
	v_exp_f32_e32 v225, v225
	v_exp_f32_e32 v226, v226
	v_exp_f32_e32 v227, v227
	v_pk_add_f32 v[190:191], v[190:191], v[188:189]
	v_pk_add_f32 v[192:193], v[192:193], v[188:189]
	v_pk_add_f32 v[224:225], v[224:225], v[188:189]
	v_pk_add_f32 v[226:227], v[226:227], v[188:189]
	v_rcp_f32_e32 v190, v190
	v_rcp_f32_e32 v191, v191
	v_rcp_f32_e32 v192, v192
	v_rcp_f32_e32 v193, v193
	v_rcp_f32_e32 v224, v224
	v_rcp_f32_e32 v225, v225
	v_rcp_f32_e32 v226, v226
	v_rcp_f32_e32 v227, v227
	v_pk_mul_f32 v[94:95], v[94:95], v[190:191]
	v_pk_mul_f32 v[96:97], v[96:97], v[192:193]
	v_pk_mul_f32 v[86:87], v[86:87], v[224:225]
	v_pk_mul_f32 v[88:89], v[88:89], v[226:227]
	v_pk_mul_f32 v[94:95], v[94:95], v[90:91]
	v_pk_mul_f32 v[96:97], v[96:97], v[92:93]
	v_pk_mul_f32 v[86:87], v[86:87], v[82:83]
	v_pk_mul_f32 v[88:89], v[88:89], v[84:85]
	v_cvt_pk_bf16_f32 v82, v94, v95
	v_cvt_pk_bf16_f32 v83, v96, v97
	v_cvt_pk_bf16_f32 v84, v86, v87
	v_cvt_pk_bf16_f32 v85, v88, v89
	v_add_co_u32_e32 v86, vcc, s67, v142
	s_nop 1
	v_addc_co_u32_e32 v87, vcc, 0, v143, vcc
	global_store_dwordx4 v[86:87], v[82:85], off
	v_pk_mul_f32 v[190:191], v[78:79], v[184:185]
	v_pk_mul_f32 v[192:193], v[80:81], v[184:185]
	v_pk_mul_f32 v[224:225], v[70:71], v[184:185]
	v_pk_mul_f32 v[226:227], v[72:73], v[184:185]
	v_exp_f32_e32 v190, v190
	v_exp_f32_e32 v191, v191
	v_exp_f32_e32 v192, v192
	v_exp_f32_e32 v193, v193
	v_exp_f32_e32 v224, v224
	v_exp_f32_e32 v225, v225
	v_exp_f32_e32 v226, v226
	v_exp_f32_e32 v227, v227
	v_pk_add_f32 v[190:191], v[190:191], v[188:189]
	v_pk_add_f32 v[192:193], v[192:193], v[188:189]
	v_pk_add_f32 v[224:225], v[224:225], v[188:189]
	v_pk_add_f32 v[226:227], v[226:227], v[188:189]
	v_rcp_f32_e32 v190, v190
	v_rcp_f32_e32 v191, v191
	v_rcp_f32_e32 v192, v192
	v_rcp_f32_e32 v193, v193
; __device__ __forceinline__ float fast_sigmoid(float x) { return __builtin_amdgcn_rcpf(1.0f + __builtin_amdgcn_exp2f(-1.4426950408889634f * x)); }
; __device__ __forceinline__ u32x4 pack8(const f32x4 v0, const f32x4 v1) { u32x4 w; w.x = cvt_pk_bf16(v0[0], v0[1]); w.y = cvt_pk_bf16(v0[2], v0[3]); w.z = cvt_pk_bf16(v1[0], v1[1]); w.w = cvt_pk_bf16(v1[2], v1[3]); return w; }
; #define PG8_BAR __builtin_amdgcn_s_barrier()
;     __device__ __forceinline__ void operator()(const f32x4 (&acc)[2][2][4][2], const Unit& u, int wr, int wc, int fr_, int fq) const {
;     ...
;                 for (int j = 0; j < 4; ++j) { const float g0 = acc[ai][0][m][0][j], g1 = acc[ai][0][m][1][j];
;                     v0[j] = g0 * fast_sigmoid(g0) * acc[ai][1][m][0][j]; v1[j] = g1 * fast_sigmoid(g1) * acc[ai][1][m][1][j]; }
;                 *(u32x4*)(Hblk + (size_t)(ai * HALF + m * 16) * BK) = pack8(v0, v1); }
; template <class Epi, class Sched, bool ALIGN_EPI = false, bool SP2 = false, bool ABLK = false, bool BBLK = false>
; __device__ __forceinline__ void gemm_phase(PG8_LAS unsigned char* lds, const Gemm g, const Sched& S, const Epi& E) {
;     ...
;         if (!has_next) break;
; #pragma unroll
;         for (int a = 0; a < 2; ++a)
; #pragma unroll
;             for (int b = 0; b < 2; ++b)
; #pragma unroll
;                 for (int m = 0; m < 4; ++m)
; #pragma unroll
;                     for (int n = 0; n < 2; ++n) acc[a][b][m][n] = (f32x4){0.f, 0.f, 0.f, 0.f};
;         cur = nxt; cA = nA; cB = nB; ++ui;
;         if constexpr (ALIGN_EPI) { if (wr == 1) PG8_BAR; }
	v_rcp_f32_e32 v224, v224
	v_rcp_f32_e32 v225, v225
	v_rcp_f32_e32 v226, v226
	v_rcp_f32_e32 v227, v227
	v_pk_mul_f32 v[78:79], v[78:79], v[190:191]
	v_pk_mul_f32 v[80:81], v[80:81], v[192:193]
	v_pk_mul_f32 v[70:71], v[70:71], v[224:225]
	v_pk_mul_f32 v[72:73], v[72:73], v[226:227]
	v_pk_mul_f32 v[78:79], v[78:79], v[74:75]
	v_pk_mul_f32 v[80:81], v[80:81], v[76:77]
	v_pk_mul_f32 v[70:71], v[70:71], v[66:67]
	v_pk_mul_f32 v[72:73], v[72:73], v[68:69]
	v_cvt_pk_bf16_f32 v66, v78, v79
	v_cvt_pk_bf16_f32 v67, v80, v81
	v_cvt_pk_bf16_f32 v68, v70, v71
	v_cvt_pk_bf16_f32 v69, v72, v73
	global_store_dwordx4 v[86:87], v[66:69], off offset:2048
	v_pk_mul_f32 v[190:191], v[62:63], v[184:185]
	v_pk_mul_f32 v[192:193], v[64:65], v[184:185]
	v_pk_mul_f32 v[224:225], v[54:55], v[184:185]
	v_pk_mul_f32 v[226:227], v[56:57], v[184:185]
	v_exp_f32_e32 v190, v190
	v_exp_f32_e32 v191, v191
	v_exp_f32_e32 v192, v192
	v_exp_f32_e32 v193, v193
	v_exp_f32_e32 v224, v224
	v_exp_f32_e32 v225, v225
	v_exp_f32_e32 v226, v226
	v_exp_f32_e32 v227, v227
	v_pk_add_f32 v[190:191], v[190:191], v[188:189]
	v_pk_add_f32 v[192:193], v[192:193], v[188:189]
	v_pk_add_f32 v[224:225], v[224:225], v[188:189]
	v_pk_add_f32 v[226:227], v[226:227], v[188:189]
	v_rcp_f32_e32 v190, v190
	v_rcp_f32_e32 v191, v191
	v_rcp_f32_e32 v192, v192
	v_rcp_f32_e32 v193, v193
	v_rcp_f32_e32 v224, v224
	v_rcp_f32_e32 v225, v225
	v_rcp_f32_e32 v226, v226
	v_rcp_f32_e32 v227, v227
	v_pk_mul_f32 v[62:63], v[62:63], v[190:191]
	v_pk_mul_f32 v[64:65], v[64:65], v[192:193]
	v_pk_mul_f32 v[54:55], v[54:55], v[224:225]
	v_pk_mul_f32 v[56:57], v[56:57], v[226:227]
	v_pk_mul_f32 v[62:63], v[62:63], v[58:59]
	v_pk_mul_f32 v[64:65], v[64:65], v[60:61]
	v_pk_mul_f32 v[54:55], v[54:55], v[50:51]
	v_pk_mul_f32 v[56:57], v[56:57], v[52:53]
	v_cvt_pk_bf16_f32 v52, v62, v63
	v_cvt_pk_bf16_f32 v53, v64, v65
	v_cvt_pk_bf16_f32 v54, v54, v55
	v_cvt_pk_bf16_f32 v55, v56, v57
	v_add_co_u32_e32 v56, vcc, s87, v142
	s_nop 1
	v_addc_co_u32_e32 v57, vcc, 0, v143, vcc
	v_add_co_u32_e32 v50, vcc, s0, v142
	s_nop 1
	s_mov_b64 s[0:1], -1
	v_addc_co_u32_e32 v51, vcc, 0, v143, vcc
	global_store_dwordx4 v[50:51], v[52:55], off offset:-4096
	v_pk_mul_f32 v[190:191], v[46:47], v[184:185]
	v_pk_mul_f32 v[192:193], v[48:49], v[184:185]
	v_pk_mul_f32 v[224:225], v[38:39], v[184:185]
	v_pk_mul_f32 v[226:227], v[40:41], v[184:185]
	v_exp_f32_e32 v190, v190
	v_exp_f32_e32 v191, v191
	v_exp_f32_e32 v192, v192
	v_exp_f32_e32 v193, v193
	v_exp_f32_e32 v224, v224
	v_exp_f32_e32 v225, v225
	v_exp_f32_e32 v226, v226
	v_exp_f32_e32 v227, v227
	v_pk_add_f32 v[190:191], v[190:191], v[188:189]
	v_pk_add_f32 v[192:193], v[192:193], v[188:189]
	v_pk_add_f32 v[224:225], v[224:225], v[188:189]
	v_pk_add_f32 v[226:227], v[226:227], v[188:189]
	v_rcp_f32_e32 v190, v190
	v_rcp_f32_e32 v191, v191
	v_rcp_f32_e32 v192, v192
	v_rcp_f32_e32 v193, v193
	v_rcp_f32_e32 v224, v224
	v_rcp_f32_e32 v225, v225
	v_rcp_f32_e32 v226, v226
	v_rcp_f32_e32 v227, v227
	v_pk_mul_f32 v[46:47], v[46:47], v[190:191]
	v_pk_mul_f32 v[48:49], v[48:49], v[192:193]
	v_pk_mul_f32 v[38:39], v[38:39], v[224:225]
	v_pk_mul_f32 v[40:41], v[40:41], v[226:227]
	v_pk_mul_f32 v[46:47], v[46:47], v[42:43]
	v_pk_mul_f32 v[48:49], v[48:49], v[44:45]
	v_pk_mul_f32 v[38:39], v[38:39], v[34:35]
	v_pk_mul_f32 v[40:41], v[40:41], v[36:37]
	v_cvt_pk_bf16_f32 v34, v46, v47
	v_cvt_pk_bf16_f32 v35, v48, v49
	v_cvt_pk_bf16_f32 v36, v38, v39
	v_cvt_pk_bf16_f32 v37, v40, v41
	s_andn2_b64 vcc, exec, s[6:7]
	global_store_dwordx4 v[56:57], v[34:37], off offset:2048
	v_pk_mul_f32 v[190:191], v[30:31], v[184:185]
	v_pk_mul_f32 v[192:193], v[32:33], v[184:185]
	v_pk_mul_f32 v[224:225], v[22:23], v[184:185]
	v_pk_mul_f32 v[226:227], v[24:25], v[184:185]
	v_exp_f32_e32 v190, v190
	v_exp_f32_e32 v191, v191
	v_exp_f32_e32 v192, v192
	v_exp_f32_e32 v193, v193
	v_exp_f32_e32 v224, v224
	v_exp_f32_e32 v225, v225
	v_exp_f32_e32 v226, v226
	v_exp_f32_e32 v227, v227
	v_pk_add_f32 v[190:191], v[190:191], v[188:189]
	v_pk_add_f32 v[192:193], v[192:193], v[188:189]
	v_pk_add_f32 v[224:225], v[224:225], v[188:189]
	v_pk_add_f32 v[226:227], v[226:227], v[188:189]
	v_rcp_f32_e32 v190, v190
	v_rcp_f32_e32 v191, v191
	v_rcp_f32_e32 v192, v192
	v_rcp_f32_e32 v193, v193
	v_rcp_f32_e32 v224, v224
	v_rcp_f32_e32 v225, v225
	v_rcp_f32_e32 v226, v226
	v_rcp_f32_e32 v227, v227
	v_pk_mul_f32 v[30:31], v[30:31], v[190:191]
	v_pk_mul_f32 v[32:33], v[32:33], v[192:193]
	v_pk_mul_f32 v[22:23], v[22:23], v[224:225]
	v_pk_mul_f32 v[24:25], v[24:25], v[226:227]
	v_pk_mul_f32 v[30:31], v[30:31], v[26:27]
	v_pk_mul_f32 v[32:33], v[32:33], v[28:29]
	v_pk_mul_f32 v[22:23], v[22:23], v[18:19]
	v_pk_mul_f32 v[24:25], v[24:25], v[20:21]
	v_cvt_pk_bf16_f32 v18, v30, v31
	v_cvt_pk_bf16_f32 v19, v32, v33
	v_cvt_pk_bf16_f32 v20, v22, v23
	v_cvt_pk_bf16_f32 v21, v24, v25
	global_store_dwordx4 v[50:51], v[18:21], off
	v_pk_mul_f32 v[190:191], v[14:15], v[184:185]
	v_pk_mul_f32 v[192:193], v[16:17], v[184:185]
	v_pk_mul_f32 v[224:225], v[6:7], v[184:185]
	v_pk_mul_f32 v[226:227], v[8:9], v[184:185]
	v_exp_f32_e32 v190, v190
	v_exp_f32_e32 v191, v191
	v_exp_f32_e32 v192, v192
	v_exp_f32_e32 v193, v193
	v_exp_f32_e32 v224, v224
	v_exp_f32_e32 v225, v225
	v_exp_f32_e32 v226, v226
	v_exp_f32_e32 v227, v227
	v_pk_add_f32 v[190:191], v[190:191], v[188:189]
	v_pk_add_f32 v[192:193], v[192:193], v[188:189]
	v_pk_add_f32 v[224:225], v[224:225], v[188:189]
	v_pk_add_f32 v[226:227], v[226:227], v[188:189]
	v_rcp_f32_e32 v190, v190
	v_rcp_f32_e32 v191, v191
	v_rcp_f32_e32 v192, v192
	v_rcp_f32_e32 v193, v193
	v_rcp_f32_e32 v224, v224
	v_rcp_f32_e32 v225, v225
	v_rcp_f32_e32 v226, v226
	v_rcp_f32_e32 v227, v227
	v_pk_mul_f32 v[14:15], v[14:15], v[190:191]
	v_pk_mul_f32 v[16:17], v[16:17], v[192:193]
	v_pk_mul_f32 v[6:7], v[6:7], v[224:225]
	v_pk_mul_f32 v[8:9], v[8:9], v[226:227]
	v_pk_mul_f32 v[14:15], v[14:15], v[10:11]
	v_pk_mul_f32 v[16:17], v[16:17], v[12:13]
	v_pk_mul_f32 v[6:7], v[6:7], v[2:3]
	v_pk_mul_f32 v[8:9], v[8:9], v[4:5]
	v_cvt_pk_bf16_f32 v2, v14, v15
	v_cvt_pk_bf16_f32 v3, v16, v17
	v_cvt_pk_bf16_f32 v4, v6, v7
	v_cvt_pk_bf16_f32 v5, v8, v9
	global_store_dwordx4 v[50:51], v[2:5], off offset:2048
	s_cbranch_vccnz .LBB0_1336
	s_andn2_b64 vcc, exec, s[4:5]
	s_cbranch_vccnz .LBB0_1335
	s_barrier
	s_branch .LBB0_1335
